# GEMM1: ping-pong stagger of the two wave groups kept across unit boundaries (re-align barrier only after the last unit, re-stagger barrier removed)
# speedup vs baseline: 1.0054x; 1.0026x over previous
.Lg1_p3:
	s_add_i32 s85, 0, 0x18000
	v_add_u32_e32 v145, s85, v142
	s_add_i32 s88, 0, 0x1c000
	ds_read_b128 v[156:159], v145
	ds_read_b128 v[160:163], v145 offset:1024
	ds_read_b128 v[164:167], v145 offset:2048
	ds_read_b128 v[168:171], v145 offset:3072
	v_add_u32_e32 v145, s88, v142
	ds_read_b128 v[172:175], v145
	ds_read_b128 v[176:179], v145 offset:1024
	ds_read_b128 v[180:183], v145 offset:2048
	ds_read_b128 v[184:187], v145 offset:3072
	s_add_u32 s62, s62, 0x40000
	s_addc_u32 s63, s63, 0
	s_mov_b32 m0, s73
	v_lshl_add_u64 v[230:231], s[62:63], 0, v[134:135]
	ds_read_b128 v[188:191], v144 offset:32768
	ds_read_b128 v[192:195], v144 offset:33792
	ds_read_b128 v[196:199], v144 offset:34816
	ds_read_b128 v[200:203], v144 offset:35840
	ds_read_b128 v[204:207], v144 offset:36864
	ds_read_b128 v[218:221], v144 offset:37888
	ds_read_b128 v[222:225], v144 offset:38912
	ds_read_b128 v[226:229], v144 offset:39936
	global_load_lds_dwordx4 v[230:231], off
	v_lshl_add_u64 v[230:231], s[62:63], 0, v[132:133]
	s_mov_b32 m0, s74
	s_nop 0
	global_load_lds_dwordx4 v[230:231], off
	s_waitcnt vmcnt(8)
	s_waitcnt lgkmcnt(0)
	s_barrier
	s_setprio 1
	s_waitcnt lgkmcnt(0)
	v_mfma_f32_16x16x32_bf16 v[124:127], v[156:159], v[188:191], v[124:127]
	v_mfma_f32_16x16x32_bf16 v[120:123], v[164:167], v[188:191], v[120:123]
	v_mfma_f32_16x16x32_bf16 v[112:115], v[156:159], v[196:199], v[112:115]
	v_mfma_f32_16x16x32_bf16 v[104:107], v[164:167], v[196:199], v[104:107]
	v_mfma_f32_16x16x32_bf16 v[96:99], v[156:159], v[204:207], v[96:99]
	v_mfma_f32_16x16x32_bf16 v[88:91], v[164:167], v[204:207], v[88:91]
	v_mfma_f32_16x16x32_bf16 v[80:83], v[156:159], v[222:225], v[80:83]
	v_mfma_f32_16x16x32_bf16 v[72:75], v[164:167], v[222:225], v[72:75]
	v_mfma_f32_16x16x32_bf16 v[124:127], v[160:163], v[192:195], v[124:127]
	v_mfma_f32_16x16x32_bf16 v[120:123], v[168:171], v[192:195], v[120:123]
	v_mfma_f32_16x16x32_bf16 v[112:115], v[160:163], v[200:203], v[112:115]
	v_mfma_f32_16x16x32_bf16 v[104:107], v[168:171], v[200:203], v[104:107]
	v_mfma_f32_16x16x32_bf16 v[96:99], v[160:163], v[218:221], v[96:99]
	v_mfma_f32_16x16x32_bf16 v[88:91], v[168:171], v[218:221], v[88:91]
	v_mfma_f32_16x16x32_bf16 v[80:83], v[160:163], v[226:229], v[80:83]
	v_mfma_f32_16x16x32_bf16 v[72:75], v[168:171], v[226:229], v[72:75]
	s_setprio 0
	s_setprio 1
	v_mfma_f32_16x16x32_bf16 v[116:119], v[172:175], v[188:191], v[116:119]
	v_mfma_f32_16x16x32_bf16 v[108:111], v[180:183], v[188:191], v[108:111]
	v_mfma_f32_16x16x32_bf16 v[100:103], v[172:175], v[196:199], v[100:103]
	v_mfma_f32_16x16x32_bf16 v[92:95], v[180:183], v[196:199], v[92:95]
	v_mfma_f32_16x16x32_bf16 v[84:87], v[172:175], v[204:207], v[84:87]
	v_mfma_f32_16x16x32_bf16 v[76:79], v[180:183], v[204:207], v[76:79]
	v_mfma_f32_16x16x32_bf16 v[68:71], v[172:175], v[222:225], v[68:71]
	v_mfma_f32_16x16x32_bf16 v[64:67], v[180:183], v[222:225], v[64:67]
	v_mfma_f32_16x16x32_bf16 v[116:119], v[176:179], v[192:195], v[116:119]
	v_mfma_f32_16x16x32_bf16 v[108:111], v[184:187], v[192:195], v[108:111]
	v_mfma_f32_16x16x32_bf16 v[100:103], v[176:179], v[200:203], v[100:103]
	v_mfma_f32_16x16x32_bf16 v[92:95], v[184:187], v[200:203], v[92:95]
	v_mfma_f32_16x16x32_bf16 v[84:87], v[176:179], v[218:221], v[84:87]
	v_mfma_f32_16x16x32_bf16 v[76:79], v[184:187], v[218:221], v[76:79]
	v_mfma_f32_16x16x32_bf16 v[68:71], v[176:179], v[226:229], v[68:71]
	v_mfma_f32_16x16x32_bf16 v[64:67], v[184:187], v[226:229], v[64:67]
	s_setprio 0
	s_barrier
	s_add_i32 s62, s85, s70
	v_lshl_add_u64 v[140:141], v[140:141], 0, s[0:1]
	s_mov_b32 m0, s62
	ds_read_b128 v[188:191], v144 offset:49152
	ds_read_b128 v[192:195], v144 offset:50176
	ds_read_b128 v[196:199], v144 offset:51200
	ds_read_b128 v[200:203], v144 offset:52224
	ds_read_b128 v[204:207], v144 offset:53248
	ds_read_b128 v[218:221], v144 offset:54272
	ds_read_b128 v[222:225], v144 offset:55296
	ds_read_b128 v[226:229], v144 offset:56320
	global_load_lds_dwordx4 v[140:141], off
	s_add_i32 m0, s62, 0x2000
	s_add_u32 s60, s60, 0x40080
	v_lshl_add_u64 v[140:141], v[146:147], 0, s[0:1]
	s_addc_u32 s61, s61, 0
	s_add_i32 s62, s88, s70
	global_load_lds_dwordx4 v[140:141], off
	v_lshl_add_u64 v[140:141], s[60:61], 0, v[148:149]
	s_mov_b32 m0, s62
	s_nop 0
	global_load_lds_dwordx4 v[140:141], off
	v_lshl_add_u64 v[140:141], s[60:61], 0, v[130:131]
	s_add_i32 m0, s62, 0x2000
	s_nop 0
	global_load_lds_dwordx4 v[140:141], off
	v_lshl_add_u64 v[140:141], v[208:209], 0, s[0:1]
	s_mov_b32 m0, s75
	s_nop 0
	global_load_lds_dwordx4 v[140:141], off
	v_lshl_add_u64 v[140:141], v[212:213], 0, s[0:1]
	s_mov_b32 m0, s76
	s_nop 0
	global_load_lds_dwordx4 v[140:141], off
	s_waitcnt vmcnt(8)
	s_waitcnt lgkmcnt(0)
	s_barrier
	s_setprio 1
	s_waitcnt lgkmcnt(0)
	v_mfma_f32_16x16x32_bf16 v[60:63], v[156:159], v[188:191], v[60:63]
	v_mfma_f32_16x16x32_bf16 v[56:59], v[164:167], v[188:191], v[56:59]
	v_mfma_f32_16x16x32_bf16 v[48:51], v[156:159], v[196:199], v[48:51]
	v_mfma_f32_16x16x32_bf16 v[40:43], v[164:167], v[196:199], v[40:43]
	v_mfma_f32_16x16x32_bf16 v[32:35], v[156:159], v[204:207], v[32:35]
	v_mfma_f32_16x16x32_bf16 v[24:27], v[164:167], v[204:207], v[24:27]
	v_mfma_f32_16x16x32_bf16 v[16:19], v[156:159], v[222:225], v[16:19]
	v_mfma_f32_16x16x32_bf16 v[8:11], v[164:167], v[222:225], v[8:11]
	v_mfma_f32_16x16x32_bf16 v[60:63], v[160:163], v[192:195], v[60:63]
	v_mfma_f32_16x16x32_bf16 v[56:59], v[168:171], v[192:195], v[56:59]
	v_mfma_f32_16x16x32_bf16 v[48:51], v[160:163], v[200:203], v[48:51]
	v_mfma_f32_16x16x32_bf16 v[40:43], v[168:171], v[200:203], v[40:43]
	v_mfma_f32_16x16x32_bf16 v[32:35], v[160:163], v[218:221], v[32:35]
	v_mfma_f32_16x16x32_bf16 v[24:27], v[168:171], v[218:221], v[24:27]
	v_mfma_f32_16x16x32_bf16 v[16:19], v[160:163], v[226:229], v[16:19]
	v_mfma_f32_16x16x32_bf16 v[8:11], v[168:171], v[226:229], v[8:11]
	s_setprio 0
	s_setprio 1
	v_mfma_f32_16x16x32_bf16 v[52:55], v[172:175], v[188:191], v[52:55]
	v_mfma_f32_16x16x32_bf16 v[44:47], v[180:183], v[188:191], v[44:47]
	v_mfma_f32_16x16x32_bf16 v[36:39], v[172:175], v[196:199], v[36:39]
	v_mfma_f32_16x16x32_bf16 v[28:31], v[180:183], v[196:199], v[28:31]
	v_mfma_f32_16x16x32_bf16 v[20:23], v[172:175], v[204:207], v[20:23]
	v_mfma_f32_16x16x32_bf16 v[12:15], v[180:183], v[204:207], v[12:15]
	v_mfma_f32_16x16x32_bf16 v[4:7], v[172:175], v[222:225], v[4:7]
	v_mfma_f32_16x16x32_bf16 v[0:3], v[180:183], v[222:225], v[0:3]
	v_mfma_f32_16x16x32_bf16 v[52:55], v[176:179], v[192:195], v[52:55]
	v_mfma_f32_16x16x32_bf16 v[44:47], v[184:187], v[192:195], v[44:47]
	v_mfma_f32_16x16x32_bf16 v[36:39], v[176:179], v[200:203], v[36:39]
	v_mfma_f32_16x16x32_bf16 v[28:31], v[184:187], v[200:203], v[28:31]
	v_mfma_f32_16x16x32_bf16 v[20:23], v[176:179], v[218:221], v[20:23]
	v_mfma_f32_16x16x32_bf16 v[12:15], v[184:187], v[218:221], v[12:15]
	v_mfma_f32_16x16x32_bf16 v[4:7], v[176:179], v[226:229], v[4:7]
	v_mfma_f32_16x16x32_bf16 v[0:3], v[184:187], v[226:229], v[0:3]
	s_setprio 0
	s_barrier
	s_add_i32 s84, s84, 2
	s_add_u32 s82, s82, 0x100
	s_addc_u32 s83, s83, 0
	s_add_u32 s58, s58, 0x100
	s_addc_u32 s59, s59, 0
	s_cmp_gt_u32 s84, 13
	s_cbranch_scc0 .LBB0_289
	s_andn2_b64 vcc, s[38:39], s[40:41]
	s_cbranch_vccz .LBB0_292
	s_barrier
.LBB0_292:
	v_lshl_or_b32 v140, s78, 8, v143
	v_ashrrev_i32_e32 v141, 31, v140
	v_lshl_add_u32 v145, s79, 8, v129
	v_lshl_add_u64 v[140:141], v[140:141], 1, s[36:37]
	v_cvt_pk_bf16_f32 v156, v124, v125
	v_cvt_pk_bf16_f32 v157, v126, v127
	v_mad_i64_i32 v[146:147], s[58:59], v145, s3, v[140:141]
	v_cvt_pk_bf16_f32 v158, v120, v121
	v_cvt_pk_bf16_f32 v159, v122, v123
	global_store_dwordx4 v[146:147], v[156:159], off sc1
	s_nop 1
	v_cvt_pk_bf16_f32 v160, v116, v117
	v_cvt_pk_bf16_f32 v161, v118, v119
	v_cvt_pk_bf16_f32 v162, v108, v109
	v_cvt_pk_bf16_f32 v163, v110, v111
	v_lshl_add_u64 v[116:117], v[146:147], 0, s[10:11]
	global_store_dwordx4 v[116:117], v[160:163], off sc1
	s_nop 1
	v_or_b32_e32 v108, 16, v145
	v_cvt_pk_bf16_f32 v164, v112, v113
	v_cvt_pk_bf16_f32 v165, v114, v115
	v_mad_i64_i32 v[108:109], s[58:59], v108, s3, v[140:141]
	v_cvt_pk_bf16_f32 v166, v104, v105
	v_cvt_pk_bf16_f32 v167, v106, v107
	global_store_dwordx4 v[108:109], v[164:167], off sc1
	s_nop 1
	v_cvt_pk_bf16_f32 v168, v100, v101
	v_cvt_pk_bf16_f32 v169, v102, v103
	v_cvt_pk_bf16_f32 v170, v92, v93
	v_cvt_pk_bf16_f32 v171, v94, v95
	v_lshl_add_u64 v[100:101], v[108:109], 0, s[10:11]
	global_store_dwordx4 v[100:101], v[168:171], off sc1
	s_nop 1
	v_or_b32_e32 v92, 32, v145
	v_cvt_pk_bf16_f32 v172, v96, v97
	v_cvt_pk_bf16_f32 v173, v98, v99
	v_mad_i64_i32 v[92:93], s[58:59], v92, s3, v[140:141]
	v_cvt_pk_bf16_f32 v174, v88, v89
	v_cvt_pk_bf16_f32 v175, v90, v91
	global_store_dwordx4 v[92:93], v[172:175], off sc1
	s_nop 1
	v_cvt_pk_bf16_f32 v176, v84, v85
	v_cvt_pk_bf16_f32 v177, v86, v87
	v_cvt_pk_bf16_f32 v178, v76, v77
	v_cvt_pk_bf16_f32 v179, v78, v79
	v_lshl_add_u64 v[84:85], v[92:93], 0, s[10:11]
	global_store_dwordx4 v[84:85], v[176:179], off sc1
	s_nop 1
	v_or_b32_e32 v76, 48, v145
	v_cvt_pk_bf16_f32 v180, v80, v81
	v_cvt_pk_bf16_f32 v181, v82, v83
	v_mad_i64_i32 v[76:77], s[58:59], v76, s3, v[140:141]
	v_cvt_pk_bf16_f32 v182, v72, v73
	v_cvt_pk_bf16_f32 v183, v74, v75
	global_store_dwordx4 v[76:77], v[180:183], off sc1
	s_nop 1
	v_cvt_pk_bf16_f32 v184, v68, v69
	v_cvt_pk_bf16_f32 v185, v70, v71
	v_cvt_pk_bf16_f32 v186, v64, v65
	v_cvt_pk_bf16_f32 v187, v66, v67
	v_lshl_add_u64 v[68:69], v[76:77], 0, s[10:11]
	global_store_dwordx4 v[68:69], v[184:187], off sc1
	s_nop 1
	v_add_u32_e32 v64, 0x80, v145
	v_cvt_pk_bf16_f32 v156, v60, v61
	v_cvt_pk_bf16_f32 v157, v62, v63
	v_mad_i64_i32 v[64:65], s[58:59], v64, s3, v[140:141]
	v_cvt_pk_bf16_f32 v158, v56, v57
	v_cvt_pk_bf16_f32 v159, v58, v59
	global_store_dwordx4 v[64:65], v[156:159], off sc1
	s_nop 1
	v_cvt_pk_bf16_f32 v160, v52, v53
	v_cvt_pk_bf16_f32 v161, v54, v55
	v_cvt_pk_bf16_f32 v162, v44, v45
	v_cvt_pk_bf16_f32 v163, v46, v47
	v_lshl_add_u64 v[52:53], v[64:65], 0, s[10:11]
	global_store_dwordx4 v[52:53], v[160:163], off sc1
	s_nop 1
	v_add_u32_e32 v44, 0x90, v145
	v_cvt_pk_bf16_f32 v164, v48, v49
	v_cvt_pk_bf16_f32 v165, v50, v51
	v_mad_i64_i32 v[44:45], s[58:59], v44, s3, v[140:141]
	v_cvt_pk_bf16_f32 v166, v40, v41
	v_cvt_pk_bf16_f32 v167, v42, v43
	global_store_dwordx4 v[44:45], v[164:167], off sc1
	s_nop 1
	v_cvt_pk_bf16_f32 v168, v36, v37
	v_cvt_pk_bf16_f32 v169, v38, v39
	v_cvt_pk_bf16_f32 v170, v28, v29
	v_cvt_pk_bf16_f32 v171, v30, v31
	v_lshl_add_u64 v[36:37], v[44:45], 0, s[10:11]
	global_store_dwordx4 v[36:37], v[168:171], off sc1
	s_nop 1
	v_add_u32_e32 v28, 0xa0, v145
	v_cvt_pk_bf16_f32 v172, v32, v33
	v_cvt_pk_bf16_f32 v173, v34, v35
	v_mad_i64_i32 v[28:29], s[58:59], v28, s3, v[140:141]
	v_cvt_pk_bf16_f32 v174, v24, v25
	v_cvt_pk_bf16_f32 v175, v26, v27
	global_store_dwordx4 v[28:29], v[172:175], off sc1
	s_nop 1
	v_cvt_pk_bf16_f32 v176, v20, v21
	v_cvt_pk_bf16_f32 v177, v22, v23
	v_cvt_pk_bf16_f32 v178, v12, v13
	v_cvt_pk_bf16_f32 v179, v14, v15
	v_lshl_add_u64 v[20:21], v[28:29], 0, s[10:11]
	global_store_dwordx4 v[20:21], v[176:179], off sc1
	s_nop 1
	v_add_u32_e32 v12, 0xb0, v145
	v_cvt_pk_bf16_f32 v180, v16, v17
	v_cvt_pk_bf16_f32 v181, v18, v19
	v_mad_i64_i32 v[12:13], s[58:59], v12, s3, v[140:141]
	v_cvt_pk_bf16_f32 v182, v8, v9
	v_cvt_pk_bf16_f32 v183, v10, v11
	global_store_dwordx4 v[12:13], v[180:183], off sc1
	s_nop 1
	v_cvt_pk_bf16_f32 v184, v4, v5
	v_lshl_add_u64 v[4:5], v[12:13], 0, s[10:11]
	v_cvt_pk_bf16_f32 v185, v6, v7
	v_cvt_pk_bf16_f32 v186, v0, v1
	v_cvt_pk_bf16_f32 v187, v2, v3
	s_andn2_b64 vcc, exec, s[40:41]
	global_store_dwordx4 v[4:5], v[184:187], off sc1
	s_nop 1
	s_mov_b64 s[40:41], -1
	s_cbranch_vccnz .LBB0_285
	s_andn2_b64 vcc, exec, s[34:35]
	s_cbranch_vccnz .LBB0_284
	s_branch .LBB0_284
